# ph6 GEMM epilogue hand-written: 8 loads of a row-group issued together, 2 groups in flight, counted vmcnt (was vmcnt(0) per load pair); plus pool d-pass ring
# speedup vs baseline: 1.0286x; 1.0214x over previous
.LBB0_1657:
	s_add_u32 s4, s92, 0xd305000
	s_addc_u32 s5, s93, 0
	s_add_u32 s8, s92, 0x12305000
	s_addc_u32 s9, s93, 0
	s_lshl_b32 s43, s0, 6
	s_lshl_b32 s3, s0, 13
	s_lshl_b32 s0, s1, 5
	s_mov_b64 s[10:11], 0x80
	s_and_b32 s12, s0, 0x60
	s_add_i32 m0, s23, 0x18000
	v_lshl_add_u64 v[8:9], v[8:9], 0, s[10:11]
	s_lshl_b32 s13, s12, 7
	s_waitcnt vmcnt(4)
	s_barrier
	global_load_lds_dwordx4 v[8:9], off
	v_lshl_add_u64 v[6:7], v[6:7], 0, s[10:11]
	s_add_i32 m0, s23, 0x1a000
	s_add_i32 s44, s23, 0x8000
	s_add_i32 s45, s23, 0xa000
	global_load_lds_dwordx4 v[6:7], off
	v_lshl_add_u64 v[4:5], v[4:5], 0, s[10:11]
	s_mov_b32 m0, s44
	s_add_u32 s0, s26, 0x80080
	global_load_lds_dwordx4 v[4:5], off
	v_lshl_add_u64 v[2:3], v[2:3], 0, s[10:11]
	s_mov_b32 m0, s45
	s_addc_u32 s1, s27, 0
	global_load_lds_dwordx4 v[2:3], off
	s_add_i32 m0, s23, 0x1c000
	v_lshl_add_u64 v[2:3], s[0:1], 0, v[130:131]
	global_load_lds_dwordx4 v[2:3], off
	v_lshl_add_u64 v[2:3], s[0:1], 0, v[132:133]
	s_add_i32 m0, s23, 0x1e000
	v_and_b32_e32 v153, 15, v0
	global_load_lds_dwordx4 v[2:3], off
	v_bfe_u32 v2, v0, 4, 2
	v_lshlrev_b32_e32 v3, 4, v2
	v_lshlrev_b32_e32 v6, 6, v0
	s_movk_i32 s0, 0x3c0
	v_lshl_or_b32 v4, v153, 6, v3
	v_and_b32_e32 v5, 32, v152
	v_and_or_b32 v3, v6, s0, v3
	v_lshl_or_b32 v155, v2, 2, s12
	v_lshlrev_b32_e32 v2, 9, v0
	v_bitop3_b32 v154, s13, v3, v5 bitop3:0xf6
	v_and_b32_e32 v2, 0x30000, v2
	v_lshlrev_b32_e32 v3, 12, v12
	v_or3_b32 v2, v10, v2, v3
	v_add_u32_e32 v136, v2, v11
	v_lshlrev_b32_e32 v2, 5, v13
	s_waitcnt vmcnt(6)
	v_and_b32_e32 v2, 0x70000, v2
	v_bitop3_b32 v4, v4, s3, v5 bitop3:0xde
	v_or3_b32 v2, v10, v2, v3
	s_add_i32 s49, 0, 0x10000
	s_add_i32 s51, 0, 0x14000
	s_waitcnt lgkmcnt(0)
	s_ashr_i32 s46, s30, 31
	s_ashr_i32 s47, s70, 31
	v_mov_b32_e32 v137, v135
	v_add_u32_e32 v138, v2, v11
	v_mov_b32_e32 v139, v135
	v_mov_b64_e32 v[140:141], 0x220
	v_mov_b64_e32 v[142:143], 0x21f
	s_movk_i32 s48, 0x45
	v_add_u32_e32 v156, s49, v154
	v_add_u32_e32 v157, 0, v4
	s_mov_b32 s50, 0xc000
	v_add_u32_e32 v158, s51, v154
	s_movk_i32 s52, 0x3fff
	s_mov_b64 s[12:13], 0x4000
	s_barrier
	s_branch .LBB0_1659
.LBB0_1659:
	s_add_i32 s41, s41, 1
	s_mul_i32 s0, s41, s46
	s_mul_hi_u32 s1, s41, s30
	s_add_i32 s1, s1, s0
	s_mul_i32 s0, s41, s30
	s_add_u32 s18, s0, s70
	s_addc_u32 s19, s1, s47
	v_cmp_gt_i64_e64 s[0:1], s[18:19], v[142:143]
	s_and_b64 vcc, exec, s[0:1]
	s_cbranch_vccnz .LBB0_1661
	s_ashr_i32 s3, s18, 31
	s_lshr_b32 s3, s3, 29
	s_add_i32 s3, s18, s3
	s_ashr_i32 s14, s3, 3
	s_and_b32 s3, s3, -8
	s_sub_i32 s3, s18, s3
	s_cmp_lt_i32 s3, 0
	s_cselect_b32 s15, s48, 0x44
	s_mul_i32 s3, s15, s3
	s_add_i32 s3, s3, s14
	s_ashr_i32 s14, s3, 31
	s_lshr_b32 s14, s14, 26
	s_add_i32 s14, s3, s14
	s_ashr_i32 s15, s14, 6
	s_lshl_b32 s15, s15, 3
	s_sub_i32 s16, 0x44, s15
	s_min_i32 s16, s16, 8
	s_abs_i32 s17, s16
	v_cvt_f32_u32_e32 v2, s17
	s_sub_i32 s21, 0, s17
	s_andn2_b32 s14, s14, 63
	s_sub_i32 s3, s3, s14
	v_rcp_iflag_f32_e32 v2, v2
	s_abs_i32 s14, s3
	s_xor_b32 s20, s3, s16
	s_ashr_i32 s20, s20, 31
	v_mul_f32_e32 v2, 0x4f7ffffe, v2
	v_cvt_u32_f32_e32 v2, v2
	s_nop 0
	v_readfirstlane_b32 s28, v2
	s_mul_i32 s21, s21, s28
	s_mul_hi_u32 s21, s28, s21
	s_add_i32 s28, s28, s21
	s_mul_hi_u32 s21, s14, s28
	s_mul_i32 s28, s21, s17
	s_sub_i32 s14, s14, s28
	s_add_i32 s29, s21, 1
	s_sub_i32 s28, s14, s17
	s_cmp_ge_u32 s14, s17
	s_cselect_b32 s21, s29, s21
	s_cselect_b32 s14, s28, s14
	s_add_i32 s28, s21, 1
	s_cmp_ge_u32 s14, s17
	s_cselect_b32 s14, s28, s21
	s_xor_b32 s14, s14, s20
	s_sub_i32 s14, s14, s20
	s_mul_i32 s16, s14, s16
	s_sub_i32 s3, s3, s16
	s_add_i32 s16, s3, s15

.LBB0_1662:
	ds_read_b128 v[144:147], v156
	ds_read_b128 v[148:151], v156 offset:1024
	ds_read_b128 v[160:163], v156 offset:2048
	ds_read_b128 v[164:167], v156 offset:3072
	s_add_u32 s26, s24, 0xfff80080
	s_addc_u32 s27, s25, -1
	s_cmp_eq_u32 s56, 28
	s_cselect_b32 s29, s3, s27
	s_cselect_b32 s28, s17, s26
	s_cselect_b32 s27, s15, s55
	s_cselect_b32 s26, s53, s54
	v_lshl_add_u64 v[184:185], s[24:25], 0, v[136:137]
	s_add_i32 m0, s23, 0xc000
	ds_read_b128 v[168:171], v157
	ds_read_b128 v[172:175], v157 offset:1024
	ds_read_b128 v[176:179], v157 offset:2048
	ds_read_b128 v[180:183], v157 offset:3072
	ds_read_b128 v[188:191], v157 offset:4096
	ds_read_b128 v[192:195], v157 offset:5120
	ds_read_b128 v[196:199], v157 offset:6144
	ds_read_b128 v[200:203], v157 offset:7168
	global_load_lds_dwordx4 v[184:185], off
	v_lshl_add_u64 v[184:185], s[24:25], 0, v[138:139]
	s_add_i32 m0, s23, 0xe000
	s_nop 0
	global_load_lds_dwordx4 v[184:185], off
	s_waitcnt lgkmcnt(8)
	s_barrier
	s_waitcnt lgkmcnt(0)
	s_setprio 1
	s_waitcnt lgkmcnt(0)
	v_mfma_f32_16x16x32_bf16 v[126:129], v[144:147], v[168:171], v[126:129]
	v_mfma_f32_16x16x32_bf16 v[122:125], v[160:163], v[168:171], v[122:125]
	v_mfma_f32_16x16x32_bf16 v[110:113], v[144:147], v[176:179], v[110:113]
	v_mfma_f32_16x16x32_bf16 v[106:109], v[160:163], v[176:179], v[106:109]
	v_mfma_f32_16x16x32_bf16 v[94:97], v[144:147], v[188:191], v[94:97]
	v_mfma_f32_16x16x32_bf16 v[90:93], v[160:163], v[188:191], v[90:93]
	v_mfma_f32_16x16x32_bf16 v[78:81], v[144:147], v[196:199], v[78:81]
	v_mfma_f32_16x16x32_bf16 v[74:77], v[160:163], v[196:199], v[74:77]
	v_mfma_f32_16x16x32_bf16 v[126:129], v[148:151], v[172:175], v[126:129]
	v_mfma_f32_16x16x32_bf16 v[122:125], v[164:167], v[172:175], v[122:125]
	v_mfma_f32_16x16x32_bf16 v[110:113], v[148:151], v[180:183], v[110:113]
	v_mfma_f32_16x16x32_bf16 v[106:109], v[164:167], v[180:183], v[106:109]
	v_mfma_f32_16x16x32_bf16 v[94:97], v[148:151], v[192:195], v[94:97]
	v_mfma_f32_16x16x32_bf16 v[90:93], v[164:167], v[192:195], v[90:93]
	v_mfma_f32_16x16x32_bf16 v[78:81], v[148:151], v[200:203], v[78:81]
	v_mfma_f32_16x16x32_bf16 v[74:77], v[164:167], v[200:203], v[74:77]
	s_setprio 0
	s_barrier
	s_add_i32 s57, s49, s37
	v_lshl_add_u64 v[184:185], s[26:27], 0, v[130:131]
	s_mov_b32 m0, s57
	ds_read_b128 v[204:207], v158
	ds_read_b128 v[208:211], v158 offset:1024
	ds_read_b128 v[212:215], v158 offset:2048
	ds_read_b128 v[216:219], v158 offset:3072
	global_load_lds_dwordx4 v[184:185], off
	v_lshl_add_u64 v[220:221], s[26:27], 0, v[132:133]
	s_add_i32 m0, s57, 0x2000
	s_nop 0
	global_load_lds_dwordx4 v[220:221], off
	s_barrier
	s_waitcnt lgkmcnt(0)
	s_setprio 1
	s_waitcnt lgkmcnt(0)
	v_mfma_f32_16x16x32_bf16 v[118:121], v[204:207], v[168:171], v[118:121]
	v_mfma_f32_16x16x32_bf16 v[114:117], v[212:215], v[168:171], v[114:117]
	v_mfma_f32_16x16x32_bf16 v[102:105], v[204:207], v[176:179], v[102:105]
	v_mfma_f32_16x16x32_bf16 v[98:101], v[212:215], v[176:179], v[98:101]
	v_mfma_f32_16x16x32_bf16 v[86:89], v[204:207], v[188:191], v[86:89]
	v_mfma_f32_16x16x32_bf16 v[82:85], v[212:215], v[188:191], v[82:85]
	v_mfma_f32_16x16x32_bf16 v[70:73], v[204:207], v[196:199], v[70:73]
	v_mfma_f32_16x16x32_bf16 v[66:69], v[212:215], v[196:199], v[66:69]
	v_mfma_f32_16x16x32_bf16 v[118:121], v[208:211], v[172:175], v[118:121]
	v_mfma_f32_16x16x32_bf16 v[114:117], v[216:219], v[172:175], v[114:117]
	v_mfma_f32_16x16x32_bf16 v[102:105], v[208:211], v[180:183], v[102:105]
	v_mfma_f32_16x16x32_bf16 v[98:101], v[216:219], v[180:183], v[98:101]
	v_mfma_f32_16x16x32_bf16 v[86:89], v[208:211], v[192:195], v[86:89]
	v_mfma_f32_16x16x32_bf16 v[82:85], v[216:219], v[192:195], v[82:85]
	v_mfma_f32_16x16x32_bf16 v[70:73], v[208:211], v[200:203], v[70:73]
	v_mfma_f32_16x16x32_bf16 v[66:69], v[216:219], v[200:203], v[66:69]
	s_setprio 0
	s_mov_b32 m0, s23
	v_lshl_add_u64 v[222:223], s[28:29], 0, v[130:131]
	s_barrier
	ds_read_b128 v[168:171], v157 offset:16384
	ds_read_b128 v[172:175], v157 offset:17408
	ds_read_b128 v[176:179], v157 offset:18432
	ds_read_b128 v[180:183], v157 offset:19456
	ds_read_b128 v[188:191], v157 offset:20480
	ds_read_b128 v[192:195], v157 offset:21504
	ds_read_b128 v[196:199], v157 offset:22528
	ds_read_b128 v[200:203], v157 offset:23552
	global_load_lds_dwordx4 v[222:223], off
	v_lshl_add_u64 v[224:225], s[28:29], 0, v[132:133]
	s_mov_b32 m0, s38
	s_nop 0
	global_load_lds_dwordx4 v[224:225], off
	s_barrier
	s_waitcnt lgkmcnt(0)
	s_setprio 1
	s_waitcnt lgkmcnt(0)
	v_mfma_f32_16x16x32_bf16 v[62:65], v[144:147], v[168:171], v[62:65]
	v_mfma_f32_16x16x32_bf16 v[58:61], v[160:163], v[168:171], v[58:61]
	v_mfma_f32_16x16x32_bf16 v[46:49], v[144:147], v[176:179], v[46:49]
	v_mfma_f32_16x16x32_bf16 v[42:45], v[160:163], v[176:179], v[42:45]
	v_mfma_f32_16x16x32_bf16 v[30:33], v[144:147], v[188:191], v[30:33]
	v_mfma_f32_16x16x32_bf16 v[26:29], v[160:163], v[188:191], v[26:29]
	v_mfma_f32_16x16x32_bf16 v[14:17], v[144:147], v[196:199], v[14:17]
	v_mfma_f32_16x16x32_bf16 v[10:13], v[160:163], v[196:199], v[10:13]
	v_mfma_f32_16x16x32_bf16 v[62:65], v[148:151], v[172:175], v[62:65]
	v_mfma_f32_16x16x32_bf16 v[58:61], v[164:167], v[172:175], v[58:61]
	v_mfma_f32_16x16x32_bf16 v[46:49], v[148:151], v[180:183], v[46:49]
	v_mfma_f32_16x16x32_bf16 v[42:45], v[164:167], v[180:183], v[42:45]
	v_mfma_f32_16x16x32_bf16 v[30:33], v[148:151], v[192:195], v[30:33]
	v_mfma_f32_16x16x32_bf16 v[26:29], v[164:167], v[192:195], v[26:29]
	v_mfma_f32_16x16x32_bf16 v[14:17], v[148:151], v[200:203], v[14:17]
	v_mfma_f32_16x16x32_bf16 v[10:13], v[164:167], v[200:203], v[10:13]
	s_setprio 0
	s_barrier
	s_add_u32 s58, s26, 0x80000
	s_addc_u32 s59, s27, 0
	s_add_i32 s57, s51, s37
	v_lshl_add_u64 v[144:145], s[58:59], 0, v[130:131]
	s_mov_b32 m0, s57
	s_nop 0
	global_load_lds_dwordx4 v[144:145], off
	v_lshl_add_u64 v[144:145], s[58:59], 0, v[132:133]
	s_add_i32 m0, s57, 0x2000
	s_nop 0
	global_load_lds_dwordx4 v[144:145], off
	s_waitcnt vmcnt(6)
	s_barrier
	s_setprio 1
	v_mfma_f32_16x16x32_bf16 v[54:57], v[204:207], v[168:171], v[54:57]
	v_mfma_f32_16x16x32_bf16 v[50:53], v[212:215], v[168:171], v[50:53]
	v_mfma_f32_16x16x32_bf16 v[38:41], v[204:207], v[176:179], v[38:41]
	v_mfma_f32_16x16x32_bf16 v[34:37], v[212:215], v[176:179], v[34:37]
	v_mfma_f32_16x16x32_bf16 v[22:25], v[204:207], v[188:191], v[22:25]
	v_mfma_f32_16x16x32_bf16 v[18:21], v[212:215], v[188:191], v[18:21]
	v_mfma_f32_16x16x32_bf16 v[6:9], v[204:207], v[196:199], v[6:9]
	v_mfma_f32_16x16x32_bf16 v[2:5], v[212:215], v[196:199], v[2:5]
	v_mfma_f32_16x16x32_bf16 v[54:57], v[208:211], v[172:175], v[54:57]
	v_mfma_f32_16x16x32_bf16 v[50:53], v[216:219], v[172:175], v[50:53]
	v_mfma_f32_16x16x32_bf16 v[38:41], v[208:211], v[180:183], v[38:41]
	v_mfma_f32_16x16x32_bf16 v[34:37], v[216:219], v[180:183], v[34:37]
	v_mfma_f32_16x16x32_bf16 v[22:25], v[208:211], v[192:195], v[22:25]
	v_mfma_f32_16x16x32_bf16 v[18:21], v[216:219], v[192:195], v[18:21]
	v_mfma_f32_16x16x32_bf16 v[6:9], v[208:211], v[200:203], v[6:9]
	v_mfma_f32_16x16x32_bf16 v[2:5], v[216:219], v[200:203], v[2:5]
	s_setprio 0
	s_add_i32 s57, 0, 0x18000
	v_add_u32_e32 v134, s57, v154
	s_barrier
	ds_read_b128 v[144:147], v134
	ds_read_b128 v[148:151], v134 offset:1024
	ds_read_b128 v[160:163], v134 offset:2048
	ds_read_b128 v[164:167], v134 offset:3072
	s_add_u32 s28, s28, 0x80000
	s_addc_u32 s29, s29, 0
	s_mov_b32 m0, s39
	v_lshl_add_u64 v[204:205], s[28:29], 0, v[130:131]
	ds_read_b128 v[168:171], v157 offset:32768
	ds_read_b128 v[172:175], v157 offset:33792
	ds_read_b128 v[176:179], v157 offset:34816
	ds_read_b128 v[180:183], v157 offset:35840
	ds_read_b128 v[188:191], v157 offset:36864
	ds_read_b128 v[192:195], v157 offset:37888
	ds_read_b128 v[196:199], v157 offset:38912
	ds_read_b128 v[200:203], v157 offset:39936
	global_load_lds_dwordx4 v[204:205], off
	v_lshl_add_u64 v[204:205], s[28:29], 0, v[132:133]
	s_mov_b32 m0, s40
	s_nop 0
	global_load_lds_dwordx4 v[204:205], off
	s_waitcnt lgkmcnt(8)
	s_barrier
	s_waitcnt lgkmcnt(0)
	s_setprio 1
	s_waitcnt lgkmcnt(0)
	v_mfma_f32_16x16x32_bf16 v[126:129], v[144:147], v[168:171], v[126:129]
	v_mfma_f32_16x16x32_bf16 v[122:125], v[160:163], v[168:171], v[122:125]
	v_mfma_f32_16x16x32_bf16 v[110:113], v[144:147], v[176:179], v[110:113]
	v_mfma_f32_16x16x32_bf16 v[106:109], v[160:163], v[176:179], v[106:109]
	v_mfma_f32_16x16x32_bf16 v[94:97], v[144:147], v[188:191], v[94:97]
	v_mfma_f32_16x16x32_bf16 v[90:93], v[160:163], v[188:191], v[90:93]
	v_mfma_f32_16x16x32_bf16 v[78:81], v[144:147], v[196:199], v[78:81]
	v_mfma_f32_16x16x32_bf16 v[74:77], v[160:163], v[196:199], v[74:77]
	v_mfma_f32_16x16x32_bf16 v[126:129], v[148:151], v[172:175], v[126:129]
	v_mfma_f32_16x16x32_bf16 v[122:125], v[164:167], v[172:175], v[122:125]
	v_mfma_f32_16x16x32_bf16 v[110:113], v[148:151], v[180:183], v[110:113]
	v_mfma_f32_16x16x32_bf16 v[106:109], v[164:167], v[180:183], v[106:109]
	v_mfma_f32_16x16x32_bf16 v[94:97], v[148:151], v[192:195], v[94:97]
	v_mfma_f32_16x16x32_bf16 v[90:93], v[164:167], v[192:195], v[90:93]
	v_mfma_f32_16x16x32_bf16 v[78:81], v[148:151], v[200:203], v[78:81]
	v_mfma_f32_16x16x32_bf16 v[74:77], v[164:167], v[200:203], v[74:77]
	s_setprio 0
	s_barrier
	s_add_i32 s28, 0, 0x1c000
	s_add_i32 s29, s57, s37
	v_add_u32_e32 v134, s28, v154
	v_lshl_add_u64 v[184:185], v[184:185], 0, s[10:11]
	s_mov_b32 m0, s29
	ds_read_b128 v[204:207], v134
	ds_read_b128 v[208:211], v134 offset:1024
	ds_read_b128 v[212:215], v134 offset:2048
	ds_read_b128 v[216:219], v134 offset:3072
	global_load_lds_dwordx4 v[184:185], off
	v_lshl_add_u64 v[184:185], v[220:221], 0, s[10:11]
	s_add_i32 m0, s29, 0x2000
	s_nop 0
	global_load_lds_dwordx4 v[184:185], off
	s_barrier
	s_waitcnt lgkmcnt(0)
	s_setprio 1
	s_waitcnt lgkmcnt(0)
	v_mfma_f32_16x16x32_bf16 v[118:121], v[204:207], v[168:171], v[118:121]
	v_mfma_f32_16x16x32_bf16 v[114:117], v[212:215], v[168:171], v[114:117]
	v_mfma_f32_16x16x32_bf16 v[102:105], v[204:207], v[176:179], v[102:105]
	v_mfma_f32_16x16x32_bf16 v[98:101], v[212:215], v[176:179], v[98:101]
	v_mfma_f32_16x16x32_bf16 v[86:89], v[204:207], v[188:191], v[86:89]
	v_mfma_f32_16x16x32_bf16 v[82:85], v[212:215], v[188:191], v[82:85]
	v_mfma_f32_16x16x32_bf16 v[70:73], v[204:207], v[196:199], v[70:73]
	v_mfma_f32_16x16x32_bf16 v[66:69], v[212:215], v[196:199], v[66:69]
	v_mfma_f32_16x16x32_bf16 v[118:121], v[208:211], v[172:175], v[118:121]
	v_mfma_f32_16x16x32_bf16 v[114:117], v[216:219], v[172:175], v[114:117]
	v_mfma_f32_16x16x32_bf16 v[102:105], v[208:211], v[180:183], v[102:105]
	v_mfma_f32_16x16x32_bf16 v[98:101], v[216:219], v[180:183], v[98:101]
	v_mfma_f32_16x16x32_bf16 v[86:89], v[208:211], v[192:195], v[86:89]
	v_mfma_f32_16x16x32_bf16 v[82:85], v[216:219], v[192:195], v[82:85]
	v_mfma_f32_16x16x32_bf16 v[70:73], v[208:211], v[200:203], v[70:73]
	v_mfma_f32_16x16x32_bf16 v[66:69], v[216:219], v[200:203], v[66:69]
	s_setprio 0
	s_mov_b32 m0, s44
	v_lshl_add_u64 v[184:185], v[222:223], 0, s[10:11]
	s_barrier
	ds_read_b128 v[168:171], v157 offset:49152
	ds_read_b128 v[172:175], v157 offset:50176
	ds_read_b128 v[176:179], v157 offset:51200
	ds_read_b128 v[180:183], v157 offset:52224
	ds_read_b128 v[188:191], v157 offset:53248
	ds_read_b128 v[192:195], v157 offset:54272
	ds_read_b128 v[196:199], v157 offset:55296
	ds_read_b128 v[200:203], v157 offset:56320
	global_load_lds_dwordx4 v[184:185], off
	v_lshl_add_u64 v[184:185], v[224:225], 0, s[10:11]
	s_mov_b32 m0, s45
	s_nop 0
	global_load_lds_dwordx4 v[184:185], off
	s_barrier
	s_waitcnt lgkmcnt(0)
	s_setprio 1
	s_waitcnt lgkmcnt(0)
	v_mfma_f32_16x16x32_bf16 v[62:65], v[144:147], v[168:171], v[62:65]
	v_mfma_f32_16x16x32_bf16 v[58:61], v[160:163], v[168:171], v[58:61]
	v_mfma_f32_16x16x32_bf16 v[46:49], v[144:147], v[176:179], v[46:49]
	v_mfma_f32_16x16x32_bf16 v[42:45], v[160:163], v[176:179], v[42:45]
	v_mfma_f32_16x16x32_bf16 v[30:33], v[144:147], v[188:191], v[30:33]
	v_mfma_f32_16x16x32_bf16 v[26:29], v[160:163], v[188:191], v[26:29]
	v_mfma_f32_16x16x32_bf16 v[14:17], v[144:147], v[196:199], v[14:17]
	v_mfma_f32_16x16x32_bf16 v[10:13], v[160:163], v[196:199], v[10:13]
	v_mfma_f32_16x16x32_bf16 v[62:65], v[148:151], v[172:175], v[62:65]
	v_mfma_f32_16x16x32_bf16 v[58:61], v[164:167], v[172:175], v[58:61]
	v_mfma_f32_16x16x32_bf16 v[46:49], v[148:151], v[180:183], v[46:49]
	v_mfma_f32_16x16x32_bf16 v[42:45], v[164:167], v[180:183], v[42:45]
	v_mfma_f32_16x16x32_bf16 v[30:33], v[148:151], v[192:195], v[30:33]
	v_mfma_f32_16x16x32_bf16 v[26:29], v[164:167], v[192:195], v[26:29]
	v_mfma_f32_16x16x32_bf16 v[14:17], v[148:151], v[200:203], v[14:17]
	v_mfma_f32_16x16x32_bf16 v[10:13], v[164:167], v[200:203], v[10:13]
	s_setprio 0
	s_barrier
	s_add_u32 s26, s26, 0x80080
	s_addc_u32 s27, s27, 0
	s_add_i32 s28, s28, s37
	v_lshl_add_u64 v[144:145], s[26:27], 0, v[130:131]
	s_mov_b32 m0, s28
	s_nop 0
	global_load_lds_dwordx4 v[144:145], off
	v_lshl_add_u64 v[144:145], s[26:27], 0, v[132:133]
	s_add_i32 m0, s28, 0x2000
	s_nop 0
	global_load_lds_dwordx4 v[144:145], off
	s_waitcnt vmcnt(6)
	s_barrier
	s_setprio 1
	v_mfma_f32_16x16x32_bf16 v[54:57], v[204:207], v[168:171], v[54:57]
	v_mfma_f32_16x16x32_bf16 v[50:53], v[212:215], v[168:171], v[50:53]
	v_mfma_f32_16x16x32_bf16 v[38:41], v[204:207], v[176:179], v[38:41]
	v_mfma_f32_16x16x32_bf16 v[34:37], v[212:215], v[176:179], v[34:37]
	v_mfma_f32_16x16x32_bf16 v[22:25], v[204:207], v[188:191], v[22:25]
	v_mfma_f32_16x16x32_bf16 v[18:21], v[212:215], v[188:191], v[18:21]
	v_mfma_f32_16x16x32_bf16 v[6:9], v[204:207], v[196:199], v[6:9]
	v_mfma_f32_16x16x32_bf16 v[2:5], v[212:215], v[196:199], v[2:5]
	v_mfma_f32_16x16x32_bf16 v[54:57], v[208:211], v[172:175], v[54:57]
	v_mfma_f32_16x16x32_bf16 v[50:53], v[216:219], v[172:175], v[50:53]
	v_mfma_f32_16x16x32_bf16 v[38:41], v[208:211], v[180:183], v[38:41]
	v_mfma_f32_16x16x32_bf16 v[34:37], v[216:219], v[180:183], v[34:37]
	v_mfma_f32_16x16x32_bf16 v[22:25], v[208:211], v[192:195], v[22:25]
	v_mfma_f32_16x16x32_bf16 v[18:21], v[216:219], v[192:195], v[18:21]
	v_mfma_f32_16x16x32_bf16 v[6:9], v[208:211], v[200:203], v[6:9]
	v_mfma_f32_16x16x32_bf16 v[2:5], v[216:219], v[200:203], v[2:5]
	s_setprio 0
	s_add_i32 s56, s56, 2
	s_add_u32 s24, s24, 0x100
	s_addc_u32 s25, s25, 0
	s_add_u32 s54, s54, 0x100
	s_addc_u32 s55, s55, 0
	s_cmp_gt_u32 s56, 29
	s_barrier
	s_cbranch_scc0 .LBB0_1662
	s_lshl_b32 s15, s2, 8
	s_add_i32 s15, s15, s43
	s_cmp_lt_u32 s2, 64
	v_or_b32_e32 v251, s15, v153
	s_cselect_b64 s[24:25], s[72:73], s[74:75]
	s_cselect_b32 s3, 0, 0x8000000
	s_sub_u32 s24, s24, s3
	s_subb_u32 s25, s25, 0
	s_add_u32 s26, s4, 0x4000
	s_addc_u32 s27, s5, 0
	v_cmp_gt_i32_e32 vcc, s42, v251
	v_lshl_or_b32 v249, s22, 8, v155
	v_lshlrev_b32_e32 v134, 13, v251
	v_lshlrev_b32_e32 v248, 12, v251
	v_lshl_add_u32 v134, v249, 2, v134
	v_lshl_add_u32 v248, v249, 1, v248
	v_lshlrev_b32_e32 v249, 2, v249
	v_add_u32_e32 v254, 0xffffc000, v251
	v_lshrrev_b32_e32 v255, 11, v251
	v_lshrrev_b32_e32 v254, 3, v254
	v_add_u32_e32 v254, 8, v254
	v_cndmask_b32_e32 v254, v254, v255, vcc
	v_mad_u32_u24 v254, v254, s50, v249
	global_load_dwordx4 v[188:191], v134, s[24:25]
	global_load_dwordx4 v[192:195], v134, s[24:25] offset:64
	global_load_dwordx4 v[196:199], v134, s[24:25] offset:512
	global_load_dwordx4 v[200:203], v134, s[24:25] offset:576
	global_load_dwordx4 v[204:207], v254, s[26:27]
	global_load_dwordx4 v[208:211], v254, s[26:27] offset:64
	global_load_dwordx4 v[212:215], v254, s[26:27] offset:512
	global_load_dwordx4 v[216:219], v254, s[26:27] offset:576
	v_add_u32_e32 v252, 0x20000, v134
	v_add_u32_e32 v255, 0x10, v251
	v_add_u32_e32 v254, 0xffffc010, v251
	v_lshrrev_b32_e32 v255, 11, v255
	v_lshrrev_b32_e32 v254, 3, v254
	v_add_u32_e32 v254, 8, v254
	v_cndmask_b32_e32 v254, v254, v255, vcc
	v_mad_u32_u24 v254, v254, s50, v249
	global_load_dwordx4 v[220:223], v252, s[24:25]
	global_load_dwordx4 v[224:227], v252, s[24:25] offset:64
	global_load_dwordx4 v[228:231], v252, s[24:25] offset:512
	global_load_dwordx4 v[232:235], v252, s[24:25] offset:576
	global_load_dwordx4 v[236:239], v254, s[26:27]
	global_load_dwordx4 v[240:243], v254, s[26:27] offset:64
	global_load_dwordx4 v[244:247], v254, s[26:27] offset:512
	global_load_dwordx4 v[144:147], v254, s[26:27] offset:576
	s_waitcnt vmcnt(8)
	v_pk_fma_f32 v[126:127], v[126:127], v[204:205], v[188:189]
	v_pk_fma_f32 v[128:129], v[128:129], v[206:207], v[190:191]
	v_pk_fma_f32 v[122:123], v[122:123], v[208:209], v[192:193]
	v_pk_fma_f32 v[124:125], v[124:125], v[210:211], v[194:195]
	v_pk_fma_f32 v[118:119], v[118:119], v[212:213], v[196:197]
	v_pk_fma_f32 v[120:121], v[120:121], v[214:215], v[198:199]
	v_pk_fma_f32 v[114:115], v[114:115], v[216:217], v[200:201]
	v_pk_fma_f32 v[116:117], v[116:117], v[218:219], v[202:203]
	v_cvt_pk_bf16_f32 v126, v126, v127
	v_cvt_pk_bf16_f32 v127, v128, v129
	v_cvt_pk_bf16_f32 v122, v122, v123
	v_cvt_pk_bf16_f32 v123, v124, v125
	v_cvt_pk_bf16_f32 v118, v118, v119
	v_cvt_pk_bf16_f32 v119, v120, v121
	v_cvt_pk_bf16_f32 v114, v114, v115
	v_cvt_pk_bf16_f32 v115, v116, v117
	global_store_dwordx2 v248, v[126:127], s[8:9]
	global_store_dwordx2 v248, v[122:123], s[8:9] offset:32
	global_store_dwordx2 v248, v[118:119], s[8:9] offset:256
	global_store_dwordx2 v248, v[114:115], s[8:9] offset:288
	v_add_u32_e32 v252, 0x40000, v134
	v_add_u32_e32 v255, 0x20, v251
	v_add_u32_e32 v254, 0xffffc020, v251
	v_lshrrev_b32_e32 v255, 11, v255
	v_lshrrev_b32_e32 v254, 3, v254
	v_add_u32_e32 v254, 8, v254
	v_cndmask_b32_e32 v254, v254, v255, vcc
	v_mad_u32_u24 v254, v254, s50, v249
	global_load_dwordx4 v[188:191], v252, s[24:25]
	global_load_dwordx4 v[192:195], v252, s[24:25] offset:64
	global_load_dwordx4 v[196:199], v252, s[24:25] offset:512
	global_load_dwordx4 v[200:203], v252, s[24:25] offset:576
	global_load_dwordx4 v[204:207], v254, s[26:27]
	global_load_dwordx4 v[208:211], v254, s[26:27] offset:64
	global_load_dwordx4 v[212:215], v254, s[26:27] offset:512
	global_load_dwordx4 v[216:219], v254, s[26:27] offset:576
	s_waitcnt vmcnt(12)
	v_pk_fma_f32 v[110:111], v[110:111], v[236:237], v[220:221]
	v_pk_fma_f32 v[112:113], v[112:113], v[238:239], v[222:223]
	v_pk_fma_f32 v[106:107], v[106:107], v[240:241], v[224:225]
	v_pk_fma_f32 v[108:109], v[108:109], v[242:243], v[226:227]
	v_pk_fma_f32 v[102:103], v[102:103], v[244:245], v[228:229]
	v_pk_fma_f32 v[104:105], v[104:105], v[246:247], v[230:231]
	v_pk_fma_f32 v[98:99], v[98:99], v[144:145], v[232:233]
	v_pk_fma_f32 v[100:101], v[100:101], v[146:147], v[234:235]
	v_add_u32_e32 v148, 0x10000, v248
	v_cvt_pk_bf16_f32 v110, v110, v111
	v_cvt_pk_bf16_f32 v111, v112, v113
	v_cvt_pk_bf16_f32 v106, v106, v107
	v_cvt_pk_bf16_f32 v107, v108, v109
	v_cvt_pk_bf16_f32 v102, v102, v103
	v_cvt_pk_bf16_f32 v103, v104, v105
	v_cvt_pk_bf16_f32 v98, v98, v99
	v_cvt_pk_bf16_f32 v99, v100, v101
	global_store_dwordx2 v148, v[110:111], s[8:9]
	global_store_dwordx2 v148, v[106:107], s[8:9] offset:32
	global_store_dwordx2 v148, v[102:103], s[8:9] offset:256
	global_store_dwordx2 v148, v[98:99], s[8:9] offset:288
	v_add_u32_e32 v252, 0x60000, v134
	v_add_u32_e32 v255, 0x30, v251
	v_add_u32_e32 v254, 0xffffc030, v251
	v_lshrrev_b32_e32 v255, 11, v255
	v_lshrrev_b32_e32 v254, 3, v254
	v_add_u32_e32 v254, 8, v254
	v_cndmask_b32_e32 v254, v254, v255, vcc
	v_mad_u32_u24 v254, v254, s50, v249
	global_load_dwordx4 v[220:223], v252, s[24:25]
	global_load_dwordx4 v[224:227], v252, s[24:25] offset:64
	global_load_dwordx4 v[228:231], v252, s[24:25] offset:512
	global_load_dwordx4 v[232:235], v252, s[24:25] offset:576
	global_load_dwordx4 v[236:239], v254, s[26:27]
	global_load_dwordx4 v[240:243], v254, s[26:27] offset:64
	global_load_dwordx4 v[244:247], v254, s[26:27] offset:512
	global_load_dwordx4 v[144:147], v254, s[26:27] offset:576
	s_waitcnt vmcnt(12)
	v_pk_fma_f32 v[94:95], v[94:95], v[204:205], v[188:189]
	v_pk_fma_f32 v[96:97], v[96:97], v[206:207], v[190:191]
	v_pk_fma_f32 v[90:91], v[90:91], v[208:209], v[192:193]
	v_pk_fma_f32 v[92:93], v[92:93], v[210:211], v[194:195]
	v_pk_fma_f32 v[86:87], v[86:87], v[212:213], v[196:197]
	v_pk_fma_f32 v[88:89], v[88:89], v[214:215], v[198:199]
	v_pk_fma_f32 v[82:83], v[82:83], v[216:217], v[200:201]
	v_pk_fma_f32 v[84:85], v[84:85], v[218:219], v[202:203]
	v_add_u32_e32 v148, 0x20000, v248
	v_cvt_pk_bf16_f32 v94, v94, v95
	v_cvt_pk_bf16_f32 v95, v96, v97
	v_cvt_pk_bf16_f32 v90, v90, v91
	v_cvt_pk_bf16_f32 v91, v92, v93
	v_cvt_pk_bf16_f32 v86, v86, v87
	v_cvt_pk_bf16_f32 v87, v88, v89
	v_cvt_pk_bf16_f32 v82, v82, v83
	v_cvt_pk_bf16_f32 v83, v84, v85
	global_store_dwordx2 v148, v[94:95], s[8:9]
	global_store_dwordx2 v148, v[90:91], s[8:9] offset:32
	global_store_dwordx2 v148, v[86:87], s[8:9] offset:256
	global_store_dwordx2 v148, v[82:83], s[8:9] offset:288
	v_add_u32_e32 v252, 0x100000, v134
	v_add_u32_e32 v255, 0x80, v251
	v_add_u32_e32 v254, 0xffffc080, v251
	v_lshrrev_b32_e32 v255, 11, v255
	v_lshrrev_b32_e32 v254, 3, v254
	v_add_u32_e32 v254, 8, v254
	v_cndmask_b32_e32 v254, v254, v255, vcc
	v_mad_u32_u24 v254, v254, s50, v249
	global_load_dwordx4 v[188:191], v252, s[24:25]
	global_load_dwordx4 v[192:195], v252, s[24:25] offset:64
	global_load_dwordx4 v[196:199], v252, s[24:25] offset:512
	global_load_dwordx4 v[200:203], v252, s[24:25] offset:576
	global_load_dwordx4 v[204:207], v254, s[26:27]
	global_load_dwordx4 v[208:211], v254, s[26:27] offset:64
	global_load_dwordx4 v[212:215], v254, s[26:27] offset:512
	global_load_dwordx4 v[216:219], v254, s[26:27] offset:576
	s_waitcnt vmcnt(12)
	v_pk_fma_f32 v[78:79], v[78:79], v[236:237], v[220:221]
	v_pk_fma_f32 v[80:81], v[80:81], v[238:239], v[222:223]
	v_pk_fma_f32 v[74:75], v[74:75], v[240:241], v[224:225]
	v_pk_fma_f32 v[76:77], v[76:77], v[242:243], v[226:227]
	v_pk_fma_f32 v[70:71], v[70:71], v[244:245], v[228:229]
	v_pk_fma_f32 v[72:73], v[72:73], v[246:247], v[230:231]
	v_pk_fma_f32 v[66:67], v[66:67], v[144:145], v[232:233]
	v_pk_fma_f32 v[68:69], v[68:69], v[146:147], v[234:235]
	v_add_u32_e32 v148, 0x30000, v248
	v_cvt_pk_bf16_f32 v78, v78, v79
	v_cvt_pk_bf16_f32 v79, v80, v81
	v_cvt_pk_bf16_f32 v74, v74, v75
	v_cvt_pk_bf16_f32 v75, v76, v77
	v_cvt_pk_bf16_f32 v70, v70, v71
	v_cvt_pk_bf16_f32 v71, v72, v73
	v_cvt_pk_bf16_f32 v66, v66, v67
	v_cvt_pk_bf16_f32 v67, v68, v69
	global_store_dwordx2 v148, v[78:79], s[8:9]
	global_store_dwordx2 v148, v[74:75], s[8:9] offset:32
	global_store_dwordx2 v148, v[70:71], s[8:9] offset:256
	global_store_dwordx2 v148, v[66:67], s[8:9] offset:288
	v_add_u32_e32 v252, 0x120000, v134
	v_add_u32_e32 v255, 0x90, v251
	v_add_u32_e32 v254, 0xffffc090, v251
	v_lshrrev_b32_e32 v255, 11, v255
	v_lshrrev_b32_e32 v254, 3, v254
	v_add_u32_e32 v254, 8, v254
	v_cndmask_b32_e32 v254, v254, v255, vcc
	v_mad_u32_u24 v254, v254, s50, v249
	global_load_dwordx4 v[220:223], v252, s[24:25]
	global_load_dwordx4 v[224:227], v252, s[24:25] offset:64
	global_load_dwordx4 v[228:231], v252, s[24:25] offset:512
	global_load_dwordx4 v[232:235], v252, s[24:25] offset:576
	global_load_dwordx4 v[236:239], v254, s[26:27]
	global_load_dwordx4 v[240:243], v254, s[26:27] offset:64
	global_load_dwordx4 v[244:247], v254, s[26:27] offset:512
	global_load_dwordx4 v[144:147], v254, s[26:27] offset:576
	s_waitcnt vmcnt(12)
	v_pk_fma_f32 v[62:63], v[62:63], v[204:205], v[188:189]
	v_pk_fma_f32 v[64:65], v[64:65], v[206:207], v[190:191]
	v_pk_fma_f32 v[58:59], v[58:59], v[208:209], v[192:193]
	v_pk_fma_f32 v[60:61], v[60:61], v[210:211], v[194:195]
	v_pk_fma_f32 v[54:55], v[54:55], v[212:213], v[196:197]
	v_pk_fma_f32 v[56:57], v[56:57], v[214:215], v[198:199]
	v_pk_fma_f32 v[50:51], v[50:51], v[216:217], v[200:201]
	v_pk_fma_f32 v[52:53], v[52:53], v[218:219], v[202:203]
	v_add_u32_e32 v148, 0x80000, v248
	v_cvt_pk_bf16_f32 v62, v62, v63
	v_cvt_pk_bf16_f32 v63, v64, v65
	v_cvt_pk_bf16_f32 v58, v58, v59
	v_cvt_pk_bf16_f32 v59, v60, v61
	v_cvt_pk_bf16_f32 v54, v54, v55
	v_cvt_pk_bf16_f32 v55, v56, v57
	v_cvt_pk_bf16_f32 v50, v50, v51
	v_cvt_pk_bf16_f32 v51, v52, v53
	global_store_dwordx2 v148, v[62:63], s[8:9]
	global_store_dwordx2 v148, v[58:59], s[8:9] offset:32
	global_store_dwordx2 v148, v[54:55], s[8:9] offset:256
	global_store_dwordx2 v148, v[50:51], s[8:9] offset:288
	v_add_u32_e32 v252, 0x140000, v134
	v_add_u32_e32 v255, 0xa0, v251
	v_add_u32_e32 v254, 0xffffc0a0, v251
	v_lshrrev_b32_e32 v255, 11, v255
	v_lshrrev_b32_e32 v254, 3, v254
	v_add_u32_e32 v254, 8, v254
	v_cndmask_b32_e32 v254, v254, v255, vcc
	v_mad_u32_u24 v254, v254, s50, v249
	global_load_dwordx4 v[188:191], v252, s[24:25]
	global_load_dwordx4 v[192:195], v252, s[24:25] offset:64
	global_load_dwordx4 v[196:199], v252, s[24:25] offset:512
	global_load_dwordx4 v[200:203], v252, s[24:25] offset:576
	global_load_dwordx4 v[204:207], v254, s[26:27]
	global_load_dwordx4 v[208:211], v254, s[26:27] offset:64
	global_load_dwordx4 v[212:215], v254, s[26:27] offset:512
	global_load_dwordx4 v[216:219], v254, s[26:27] offset:576
	s_waitcnt vmcnt(12)
	v_pk_fma_f32 v[46:47], v[46:47], v[236:237], v[220:221]
	v_pk_fma_f32 v[48:49], v[48:49], v[238:239], v[222:223]
	v_pk_fma_f32 v[42:43], v[42:43], v[240:241], v[224:225]
	v_pk_fma_f32 v[44:45], v[44:45], v[242:243], v[226:227]
	v_pk_fma_f32 v[38:39], v[38:39], v[244:245], v[228:229]
	v_pk_fma_f32 v[40:41], v[40:41], v[246:247], v[230:231]
	v_pk_fma_f32 v[34:35], v[34:35], v[144:145], v[232:233]
	v_pk_fma_f32 v[36:37], v[36:37], v[146:147], v[234:235]
	v_add_u32_e32 v148, 0x90000, v248
	v_cvt_pk_bf16_f32 v46, v46, v47
	v_cvt_pk_bf16_f32 v47, v48, v49
	v_cvt_pk_bf16_f32 v42, v42, v43
	v_cvt_pk_bf16_f32 v43, v44, v45
	v_cvt_pk_bf16_f32 v38, v38, v39
	v_cvt_pk_bf16_f32 v39, v40, v41
	v_cvt_pk_bf16_f32 v34, v34, v35
	v_cvt_pk_bf16_f32 v35, v36, v37
	global_store_dwordx2 v148, v[46:47], s[8:9]
	global_store_dwordx2 v148, v[42:43], s[8:9] offset:32
	global_store_dwordx2 v148, v[38:39], s[8:9] offset:256
	global_store_dwordx2 v148, v[34:35], s[8:9] offset:288
	v_add_u32_e32 v252, 0x160000, v134
	v_add_u32_e32 v255, 0xb0, v251
	v_add_u32_e32 v254, 0xffffc0b0, v251
	v_lshrrev_b32_e32 v255, 11, v255
	v_lshrrev_b32_e32 v254, 3, v254
	v_add_u32_e32 v254, 8, v254
	v_cndmask_b32_e32 v254, v254, v255, vcc
	v_mad_u32_u24 v254, v254, s50, v249
	global_load_dwordx4 v[220:223], v252, s[24:25]
	global_load_dwordx4 v[224:227], v252, s[24:25] offset:64
	global_load_dwordx4 v[228:231], v252, s[24:25] offset:512
	global_load_dwordx4 v[232:235], v252, s[24:25] offset:576
	global_load_dwordx4 v[236:239], v254, s[26:27]
	global_load_dwordx4 v[240:243], v254, s[26:27] offset:64
	global_load_dwordx4 v[244:247], v254, s[26:27] offset:512
	global_load_dwordx4 v[144:147], v254, s[26:27] offset:576
	s_waitcnt vmcnt(12)
	v_pk_fma_f32 v[30:31], v[30:31], v[204:205], v[188:189]
	v_pk_fma_f32 v[32:33], v[32:33], v[206:207], v[190:191]
	v_pk_fma_f32 v[26:27], v[26:27], v[208:209], v[192:193]
	v_pk_fma_f32 v[28:29], v[28:29], v[210:211], v[194:195]
	v_pk_fma_f32 v[22:23], v[22:23], v[212:213], v[196:197]
	v_pk_fma_f32 v[24:25], v[24:25], v[214:215], v[198:199]
	v_pk_fma_f32 v[18:19], v[18:19], v[216:217], v[200:201]
	v_pk_fma_f32 v[20:21], v[20:21], v[218:219], v[202:203]
	v_add_u32_e32 v148, 0xa0000, v248
	v_cvt_pk_bf16_f32 v30, v30, v31
	v_cvt_pk_bf16_f32 v31, v32, v33
	v_cvt_pk_bf16_f32 v26, v26, v27
	v_cvt_pk_bf16_f32 v27, v28, v29
	v_cvt_pk_bf16_f32 v22, v22, v23
	v_cvt_pk_bf16_f32 v23, v24, v25
	v_cvt_pk_bf16_f32 v18, v18, v19
	v_cvt_pk_bf16_f32 v19, v20, v21
	global_store_dwordx2 v148, v[30:31], s[8:9]
	global_store_dwordx2 v148, v[26:27], s[8:9] offset:32
	global_store_dwordx2 v148, v[22:23], s[8:9] offset:256
	global_store_dwordx2 v148, v[18:19], s[8:9] offset:288
	s_waitcnt vmcnt(4)
	v_pk_fma_f32 v[14:15], v[14:15], v[236:237], v[220:221]
	v_pk_fma_f32 v[16:17], v[16:17], v[238:239], v[222:223]
	v_pk_fma_f32 v[10:11], v[10:11], v[240:241], v[224:225]
	v_pk_fma_f32 v[12:13], v[12:13], v[242:243], v[226:227]
	v_pk_fma_f32 v[6:7], v[6:7], v[244:245], v[228:229]
	v_pk_fma_f32 v[8:9], v[8:9], v[246:247], v[230:231]
	v_pk_fma_f32 v[2:3], v[2:3], v[144:145], v[232:233]
	v_pk_fma_f32 v[4:5], v[4:5], v[146:147], v[234:235]
	v_add_u32_e32 v148, 0xb0000, v248
	v_cvt_pk_bf16_f32 v14, v14, v15
	v_cvt_pk_bf16_f32 v15, v16, v17
	v_cvt_pk_bf16_f32 v10, v10, v11
	v_cvt_pk_bf16_f32 v11, v12, v13
	v_cvt_pk_bf16_f32 v6, v6, v7
	v_cvt_pk_bf16_f32 v7, v8, v9
	v_cvt_pk_bf16_f32 v2, v2, v3
	v_cvt_pk_bf16_f32 v3, v4, v5
	global_store_dwordx2 v148, v[14:15], s[8:9]
	global_store_dwordx2 v148, v[10:11], s[8:9] offset:32
	global_store_dwordx2 v148, v[6:7], s[8:9] offset:256
	global_store_dwordx2 v148, v[2:3], s[8:9] offset:288
	s_and_b64 vcc, exec, s[0:1]
	s_mov_b32 s22, s14
	s_mov_b32 s2, s16
	s_mov_b64 s[26:27], s[20:21]
	s_mov_b64 s[24:25], s[18:19]
	s_cbranch_vccnz .LBB0_1695
	s_branch .LBB0_1659
